# grid barrier: XCD leader no longer writes the per-XCD relay word (nobody reads it), so it does not wait for that atomic before the next phase
# baseline (speedup 1.0000x reference)
; DI unsigned xb_ld(unsigned* p) { return __hip_atomic_load(p, __ATOMIC_RELAXED, __HIP_MEMORY_SCOPE_AGENT); }
; DI unsigned xb_add(unsigned* p, unsigned v) { return __hip_atomic_fetch_add(p, v, __ATOMIC_RELAXED, __HIP_MEMORY_SCOPE_AGENT); }
; #define XB_SPIN(cond, bar) do { unsigned _sp = 0; while (cond) { __builtin_amdgcn_s_sleep(1); \
;     if ((++_sp & 255u) == 0u) { if (xb_ld(&(bar)[XB_TMO])) break; if (_sp > XB_SPIN_CAP) { atomicAdd(&(bar)[XB_TMO], 1u); break; } } } } while (0)
; DI void xcd_barrier(unsigned* bar, const unsigned x, volatile LAS unsigned* st, const int tid) {
;     ...
;       const unsigned og = xb_add(&bar[XB_TOP], 1u);
;       const unsigned tg = og / nx;
;       if (og + 1u == (tg + 1u) * nx) xb_add(&bar[XB_TOPGEN], 1u);
;       else XB_SPIN(xb_ld(&bar[XB_TOPGEN]) == tg, bar);
;       __builtin_amdgcn_fence(__ATOMIC_ACQUIRE, "agent");
;       xb_add(&bar[XB_XGEN(x)], 1u);
;       asm volatile("s_waitcnt vmcnt(0)" ::: "memory");
.LBB0_1311:
	s_bcnt1_i32_b64 s2, s[2:3]
	v_mov_b32_e32 v0, s2
	v_readlane_b32 s2, v252, 54
	v_readlane_b32 s3, v252, 55
	s_nop 4
	s_getpc_b64 s[98:99]
